# grid barrier release flattened: XCD leaders add to the top counter after their L2 writeback and every workgroup polls that counter directly (no top-generation hop, no per-XCD generation hop)
# speedup vs baseline: 1.0060x; 1.0045x over previous
.LBB0_44:
	v_readlane_b32 s4, v252, 8
	v_readlane_b32 s5, v252, 9
	v_mov_b32_e32 v1, 1
	v_sub_u32_e32 v4, 0, v2
	s_nop 2
	global_atomic_add v3, v145, v1, s[4:5] sc0
	v_cvt_f32_u32_e32 v1, v2
	v_rcp_iflag_f32_e32 v1, v1
	s_nop 0
	v_mul_f32_e32 v1, 0x4f7ffffe, v1
	v_cvt_u32_f32_e32 v1, v1
	v_mul_lo_u32 v4, v4, v1
	v_mul_hi_u32 v4, v1, v4
	v_add_u32_e32 v1, v1, v4
	s_waitcnt vmcnt(0)
	v_mul_hi_u32 v1, v3, v1
	v_mul_lo_u32 v4, v1, v2
	v_sub_u32_e32 v4, v3, v4
	v_add_u32_e32 v5, 1, v1
	v_cmp_ge_u32_e32 vcc, v4, v2
	v_add_u32_e32 v3, 1, v3
	s_nop 0
	v_cndmask_b32_e32 v1, v1, v5, vcc
	v_sub_u32_e32 v5, v4, v2
	v_cndmask_b32_e32 v4, v4, v5, vcc
	v_add_u32_e32 v5, 1, v1
	v_cmp_ge_u32_e32 vcc, v4, v2
	s_nop 1
	v_cndmask_b32_e32 v1, v1, v5, vcc
	v_mul_lo_u32 v4, v2, v1
	v_add_u32_e32 v2, v4, v2
	v_cmp_ne_u32_e32 vcc, v3, v2
	s_waitcnt lgkmcnt(0)
	v_add_u32_e32 v1, 1, v1
	v_mul_lo_u32 v4, v1, v0
	s_cbranch_vccnz .Lxb_poll
	buffer_wbl2 sc1
	s_waitcnt vmcnt(0)
	v_mov_b32_e32 v5, 1
	v_readlane_b32 s4, v252, 12
	v_readlane_b32 s5, v252, 13
	s_nop 4
	global_atomic_add v145, v5, s[4:5]
.Lxb_poll:
	v_readlane_b32 s4, v252, 12
	v_readlane_b32 s5, v252, 13
	s_mov_b32 s36, 0
	s_nop 4
.Lxb_spin:
	global_load_dword v5, v145, s[4:5] sc1
	s_add_i32 s36, s36, 1
	s_waitcnt vmcnt(0)
	v_cmp_lt_u32_e32 vcc, v5, v4
	s_cbranch_vccz .Lxb_done
	s_sleep 1
	s_cmp_lt_u32 s36, 0x40000
	s_cbranch_scc1 .Lxb_spin
.Lxb_done:
	buffer_inv sc1
	s_waitcnt vmcnt(0)
